# v49: v46 + prep and first pre-norm phases write-through with flat barriers
# baseline (speedup 1.0000x reference)
.LBB0_276:
	s_cmp_lt_i32 s59, 2
	s_barrier
	s_cbranch_scc1 .LBB0_330
	s_waitcnt vmcnt(0)
	s_barrier
	s_and_saveexec_b64 s[2:3], s[0:1]
	s_cbranch_execz .LBB0_329
	s_waitcnt vmcnt(0) lgkmcnt(0)
	v_mov_b32_e32 v241, 0
	v_lshlrev_b32_e64 v254, 8, s31
	v_mov_b32_e32 v247, 1
	v_mov_b32_e32 v246, 0x3600
	global_atomic_add v248, v246, v247, s[60:61] sc0
	buffer_inv sc1
